# second slot converts FFN down weights of both layers and the mLSTM out-proj; first slot out-proj, FFN up both layers, mLSTM in-proj
# speedup vs baseline: 1.0026x; 1.0001x over previous
; template <class F> DI void tr_items(const F& f, int Kdst, int Nrows, bf16_t* WT, LAS float* scr, int gw, int NGW, int lane, int& cum) {
;     const int nblk = Nrows / 32, nitems = (Kdst / 64) * nblk;
;     int first = (gw - cum) % NGW; if (first < 0) first += NGW; cum = (cum + nitems) % NGW;
;     for (int item = first; item < nitems; item += NGW) {
; DI void phase_prologue(int wv, const ArgP a, LAS unsigned char* lds, int parts) {
;     ...
;         { FWP f{a.in(26) + (size_t)l * 2816 * 1024, 1024}; tr_items(f, 2816, 1024, (bf16_t*)(ws + (l ? O_WDNT1 : O_WDNT0)), scr, gw, NGW, lane, cum); }
.LBB0_297:
	s_or_b64 exec, exec, s[16:17]
	s_add_i32 s0, s42, 0xb00
	s_ashr_i32 s16, s0, 31
	s_abs_i32 s0, s0
	s_mul_hi_u32 s17, s0, s25
	s_mul_i32 s17, s17, s15
	s_sub_i32 s0, s0, s17
	s_xor_b64 s[4:5], s[6:7], -1
	s_sub_i32 s17, s0, s15
	s_cmp_ge_u32 s0, s15
	s_cselect_b32 s0, s17, s0
	s_sub_i32 s17, s0, s15
	s_cmp_ge_u32 s0, s15
	s_cselect_b32 s0, s17, s0
	s_xor_b32 s0, s0, s16
	s_sub_i32 s20, s0, s16
	v_subrev_u32_e32 v4, s20, v0
	v_sub_u32_e32 v6, 0, v4
	v_ashrrev_i32_e32 v5, 31, v4
	v_max_i32_e32 v4, v4, v6
	v_mul_hi_u32 v6, v4, s25
	v_mul_lo_u32 v6, v6, s15
	v_sub_u32_e32 v4, v4, v6
	v_subrev_u32_e32 v6, s15, v4
	v_cmp_le_u32_e32 vcc, s15, v4
	s_nop 1
	v_cndmask_b32_e32 v4, v4, v6, vcc
	v_subrev_u32_e32 v6, s15, v4
	v_cmp_le_u32_e32 vcc, s15, v4
	s_nop 1
	v_cndmask_b32_e32 v4, v4, v6, vcc
	v_xor_b32_e32 v4, v4, v5
	v_sub_u32_e32 v4, v4, v5
	v_ashrrev_i32_e32 v5, 31, v4
	v_and_b32_e32 v5, s14, v5
	v_add_u32_e32 v8, v5, v4
	v_cmp_gt_i32_e32 vcc, s37, v8
	s_and_b64 vcc, vcc, s[98:99]
	s_and_saveexec_b64 s[16:17], vcc
	s_cbranch_execz .LBB0_293
	s_load_dwordx2 s[18:19], s[2:3], 0xd0
	s_mul_i32 s0, s43, 0xb00000
	v_mul_lo_u32 v34, v8, s39
	s_mul_i32 s21, s14, 0x16000
	v_lshl_add_u32 v35, v8, 5, v18
	s_waitcnt lgkmcnt(0)
	s_add_u32 s18, s18, s0
	s_addc_u32 s19, s19, 0
	s_and_b64 s[6:7], s[6:7], exec
	s_cselect_b32 s0, s38, 0xb00000
	v_lshl_add_u64 v[4:5], v[2:3], 0, s[0:1]
	s_mov_b64 s[6:7], 0
